# v14: prompt attention items remapped so the 8 waves of a CU take 8 consecutive query groups of one (b,head)
# baseline (speedup 1.0000x reference)
.LBB0_964:
	s_or_b64 exec, exec, s[40:41]
	v_readfirstlane_b32 s40, v2
	s_abs_i32 s41, s40
	s_mul_hi_u32 s72, s41, s51
	s_mul_i32 s76, s72, s33
	s_sub_i32 s41, s41, s76
	s_ashr_i32 s77, s40, 31
	s_add_i32 s76, s72, 1
	s_sub_i32 s78, s41, s33
	s_cmp_ge_u32 s41, s33
	s_cselect_b32 s72, s76, s72
	s_cselect_b32 s41, s78, s41
	s_add_i32 s76, s72, 1
	s_cmp_ge_u32 s41, s33
	s_cselect_b32 s41, s76, s72
	s_xor_b32 s79, s41, s77
	s_sub_i32 s72, s79, s77
	s_mul_i32 s41, s72, s33
	s_sub_i32 s78, s40, s41
	s_mov_b64 s[40:41], -1
	s_and_b64 vcc, exec, s[54:55]
	s_cbranch_vccz .LBB0_966
	s_lshr_b32 s40, s78, 3
	s_mul_i32 s40, s40, 0x780
	s_and_b32 s76, s78, 7
	s_add_i32 s76, s76, s40
	s_lshl_b32 s40, s47, 3
	s_add_i32 s76, s76, s40
	s_mov_b64 s[40:41], 0

.LBB0_1074:
	s_or_b64 exec, exec, s[40:41]
	v_readfirstlane_b32 s40, v2
	s_abs_i32 s41, s40
	s_mul_hi_u32 s68, s41, s51
	s_mul_i32 s74, s68, s33
	s_sub_i32 s41, s41, s74
	s_ashr_i32 s69, s40, 31
	s_add_i32 s74, s68, 1
	s_sub_i32 s76, s41, s33
	s_cmp_ge_u32 s41, s33
	s_cselect_b32 s68, s74, s68
	s_cselect_b32 s41, s76, s41
	s_add_i32 s74, s68, 1
	s_cmp_ge_u32 s41, s33
	s_cselect_b32 s41, s74, s68
	s_xor_b32 s77, s41, s69
	s_sub_i32 s74, s77, s69
	s_mul_i32 s41, s74, s33
	s_sub_i32 s76, s40, s41
	s_mov_b64 s[40:41], -1
	s_and_b64 vcc, exec, s[54:55]
	s_cbranch_vccz .LBB0_1076
	s_lshr_b32 s40, s76, 3
	s_mul_i32 s40, s40, 0x780
	s_and_b32 s68, s76, 7
	s_add_i32 s68, s68, s40
	s_lshl_b32 s40, s47, 3
	s_add_i32 s68, s68, s40
	s_mov_b64 s[40:41], 0
